# v58 + final RMSNorm loop software-pipelined (next row's loads in flight, two working register sets)
# speedup vs baseline: 1.0015x; 1.0015x over previous
.LBB0_2791:
	s_mov_b32 s16, 0
	s_cmpk_lt_i32 s7, 0x2000
	s_cselect_b32 s0, s5, s4
	s_add_i32 s0, s0, s7
	s_mov_b32 s12, s0
	s_mov_b32 s17, s7
	s_ashr_i32 s1, s0, 31
	s_lshl_b64 s[8:9], s[0:1], 2
	s_add_u32 s8, s2, s8
	s_addc_u32 s9, s3, s9
	global_load_dword v23, v17, s[8:9]
	s_lshl_b64 s[10:11], s[0:1], 11
	v_lshl_add_u64 v[48:49], v[18:19], 0, s[10:11]
	global_load_dwordx2 v[26:27], v[48:49], off
	global_load_dwordx2 v[28:29], v[48:49], off offset:512
	global_load_dwordx2 v[30:31], v[48:49], off offset:1024
	global_load_dwordx2 v[32:33], v[48:49], off offset:1536
	s_add_i32 s7, s7, 0x100
	s_cmpk_gt_i32 s17, 0x1fff
	s_cbranch_scc1 .Lfn_lastA
	s_cmpk_lt_i32 s7, 0x2000
	s_cselect_b32 s0, s5, s4
	s_add_i32 s0, s0, s7
	s_mov_b32 s13, s0
	s_mov_b32 s18, s7
	s_ashr_i32 s1, s0, 31
	s_lshl_b64 s[8:9], s[0:1], 2
	s_add_u32 s8, s2, s8
	s_addc_u32 s9, s3, s9
	global_load_dword v51, v17, s[8:9]
	s_lshl_b64 s[10:11], s[0:1], 11
	v_lshl_add_u64 v[48:49], v[18:19], 0, s[10:11]
	global_load_dwordx2 v[54:55], v[48:49], off
	global_load_dwordx2 v[56:57], v[48:49], off offset:512
	global_load_dwordx2 v[58:59], v[48:49], off offset:1024
	global_load_dwordx2 v[60:61], v[48:49], off offset:1536
	s_add_i32 s7, s7, 0x100
	s_waitcnt vmcnt(5)
	s_branch .Lfn_procA
.Lfn_lastA:
	s_mov_b32 s16, 1
	s_waitcnt vmcnt(0)
	s_branch .Lfn_procA
.Lfn_topA:
	s_cmpk_gt_i32 s17, 0x1fff
	s_cbranch_scc1 .Lfn_lastA
	s_cmpk_lt_i32 s7, 0x2000
	s_cselect_b32 s0, s5, s4
	s_add_i32 s0, s0, s7
	s_mov_b32 s13, s0
	s_mov_b32 s18, s7
	s_ashr_i32 s1, s0, 31
	s_lshl_b64 s[8:9], s[0:1], 2
	s_add_u32 s8, s2, s8
	s_addc_u32 s9, s3, s9
	global_load_dword v51, v17, s[8:9]
	s_lshl_b64 s[10:11], s[0:1], 11
	v_lshl_add_u64 v[48:49], v[18:19], 0, s[10:11]
	global_load_dwordx2 v[54:55], v[48:49], off
	global_load_dwordx2 v[56:57], v[48:49], off offset:512
	global_load_dwordx2 v[58:59], v[48:49], off offset:1024
	global_load_dwordx2 v[60:61], v[48:49], off offset:1536
	s_add_i32 s7, s7, 0x100
	s_waitcnt vmcnt(9)
.Lfn_procA:
	s_mov_b32 s0, s12
	s_ashr_i32 s1, s0, 31
	s_lshl_b64 s[0:1], s[0:1], 12
	v_lshl_add_u64 v[40:41], v[20:21], 0, s[0:1]
	v_lshlrev_b32_e32 v24, 16, v26
	v_fmamk_f32 v23, v23, 0x3a800000, v16
	v_mul_f32_e32 v42, 0x4f800000, v23
	v_cmp_gt_f32_e32 vcc, s6, v23
	v_and_b32_e32 v25, 0xffff0000, v26
	v_lshlrev_b32_e32 v26, 16, v27
	v_cndmask_b32_e32 v23, v23, v42, vcc
	v_sqrt_f32_e32 v42, v23
	v_and_b32_e32 v27, 0xffff0000, v27
	v_lshlrev_b32_e32 v34, 16, v28
	v_and_b32_e32 v35, 0xffff0000, v28
	v_add_u32_e32 v44, -1, v42
	v_add_u32_e32 v43, 1, v42
	v_fma_f32 v45, -v44, v42, v23
	v_fma_f32 v46, -v43, v42, v23
	v_cmp_ge_f32_e64 s[0:1], 0, v45
	v_lshlrev_b32_e32 v28, 16, v29
	v_and_b32_e32 v29, 0xffff0000, v29
	v_cndmask_b32_e64 v42, v42, v44, s[0:1]
	v_cmp_lt_f32_e64 s[0:1], 0, v46
	v_lshlrev_b32_e32 v36, 16, v30
	v_and_b32_e32 v37, 0xffff0000, v30
	v_cndmask_b32_e64 v42, v42, v43, s[0:1]
	v_mul_f32_e32 v43, 0x37800000, v42
	v_cndmask_b32_e32 v42, v42, v43, vcc
	v_cmp_class_f32_e32 vcc, v23, v22
	v_lshlrev_b32_e32 v30, 16, v31
	v_and_b32_e32 v31, 0xffff0000, v31
	v_cndmask_b32_e32 v23, v42, v23, vcc
	v_div_scale_f32 v42, s[0:1], v23, v23, 1.0
	v_rcp_f32_e32 v44, v42
	v_div_scale_f32 v43, vcc, 1.0, v23, 1.0
	v_lshlrev_b32_e32 v38, 16, v32
	v_fma_f32 v45, -v42, v44, 1.0
	v_fmac_f32_e32 v44, v45, v44
	v_mul_f32_e32 v45, v43, v44
	v_fma_f32 v46, -v42, v45, v43
	v_fmac_f32_e32 v45, v46, v44
	v_fma_f32 v42, -v42, v45, v43
	v_div_fmas_f32 v42, v42, v44, v45
	v_div_fixup_f32 v42, v42, v23, 1.0
	v_and_b32_e32 v39, 0xffff0000, v32
	v_lshlrev_b32_e32 v32, 16, v33
	v_and_b32_e32 v33, 0xffff0000, v33
	v_pk_mul_f32 v[24:25], v[42:43], v[24:25] op_sel_hi:[0,1]
	v_pk_mul_f32 v[26:27], v[42:43], v[26:27] op_sel_hi:[0,1]
	v_pk_mul_f32 v[34:35], v[42:43], v[34:35] op_sel_hi:[0,1]
	v_pk_mul_f32 v[28:29], v[42:43], v[28:29] op_sel_hi:[0,1]
	v_pk_mul_f32 v[36:37], v[42:43], v[36:37] op_sel_hi:[0,1]
	v_pk_mul_f32 v[44:45], v[42:43], v[30:31] op_sel_hi:[0,1]
	v_pk_mul_f32 v[46:47], v[42:43], v[38:39] op_sel_hi:[0,1]
	v_pk_mul_f32 v[38:39], v[42:43], v[32:33] op_sel_hi:[0,1]
	v_pk_mul_f32 v[26:27], v[2:3], v[26:27]
	v_pk_mul_f32 v[24:25], v[0:1], v[24:25]
	v_pk_mul_f32 v[30:31], v[6:7], v[28:29]
	v_pk_mul_f32 v[28:29], v[4:5], v[34:35]
	v_pk_mul_f32 v[34:35], v[10:11], v[44:45]
	v_pk_mul_f32 v[32:33], v[8:9], v[36:37]
	v_pk_mul_f32 v[38:39], v[14:15], v[38:39]
	v_pk_mul_f32 v[36:37], v[12:13], v[46:47]
	global_store_dwordx4 v[40:41], v[24:27], off
	global_store_dwordx4 v[40:41], v[28:31], off offset:1024
	global_store_dwordx4 v[40:41], v[32:35], off offset:2048
	global_store_dwordx4 v[40:41], v[36:39], off offset:3072
	s_cmp_lg_u32 s16, 0
	s_cbranch_scc1 .LBB0_2792
	s_cmpk_gt_i32 s18, 0x1fff
	s_cbranch_scc1 .Lfn_lastB
	s_cmpk_lt_i32 s7, 0x2000
	s_cselect_b32 s0, s5, s4
	s_add_i32 s0, s0, s7
	s_mov_b32 s12, s0
	s_mov_b32 s17, s7
	s_ashr_i32 s1, s0, 31
	s_lshl_b64 s[8:9], s[0:1], 2
	s_add_u32 s8, s2, s8
	s_addc_u32 s9, s3, s9
	global_load_dword v23, v17, s[8:9]
	s_lshl_b64 s[10:11], s[0:1], 11
	v_lshl_add_u64 v[48:49], v[18:19], 0, s[10:11]
	global_load_dwordx2 v[26:27], v[48:49], off
	global_load_dwordx2 v[28:29], v[48:49], off offset:512
	global_load_dwordx2 v[30:31], v[48:49], off offset:1024
	global_load_dwordx2 v[32:33], v[48:49], off offset:1536
	s_add_i32 s7, s7, 0x100
	s_waitcnt vmcnt(9)
	s_branch .Lfn_procB
.Lfn_lastB:
	s_mov_b32 s16, 1
	s_waitcnt vmcnt(0)
.Lfn_procB:
	s_mov_b32 s0, s13
	s_ashr_i32 s1, s0, 31
	s_lshl_b64 s[0:1], s[0:1], 12
	v_lshl_add_u64 v[68:69], v[20:21], 0, s[0:1]
	v_lshlrev_b32_e32 v52, 16, v54
	v_fmamk_f32 v51, v51, 0x3a800000, v16
	v_mul_f32_e32 v70, 0x4f800000, v51
	v_cmp_gt_f32_e32 vcc, s6, v51
	v_and_b32_e32 v53, 0xffff0000, v54
	v_lshlrev_b32_e32 v54, 16, v55
	v_cndmask_b32_e32 v51, v51, v70, vcc
	v_sqrt_f32_e32 v70, v51
	v_and_b32_e32 v55, 0xffff0000, v55
	v_lshlrev_b32_e32 v62, 16, v56
	v_and_b32_e32 v63, 0xffff0000, v56
	v_add_u32_e32 v72, -1, v70
	v_add_u32_e32 v71, 1, v70
	v_fma_f32 v73, -v72, v70, v51
	v_fma_f32 v74, -v71, v70, v51
	v_cmp_ge_f32_e64 s[0:1], 0, v73
	v_lshlrev_b32_e32 v56, 16, v57
	v_and_b32_e32 v57, 0xffff0000, v57
	v_cndmask_b32_e64 v70, v70, v72, s[0:1]
	v_cmp_lt_f32_e64 s[0:1], 0, v74
	v_lshlrev_b32_e32 v64, 16, v58
	v_and_b32_e32 v65, 0xffff0000, v58
	v_cndmask_b32_e64 v70, v70, v71, s[0:1]
	v_mul_f32_e32 v71, 0x37800000, v70
	v_cndmask_b32_e32 v70, v70, v71, vcc
	v_cmp_class_f32_e32 vcc, v51, v22
	v_lshlrev_b32_e32 v58, 16, v59
	v_and_b32_e32 v59, 0xffff0000, v59
	v_cndmask_b32_e32 v51, v70, v51, vcc
	v_div_scale_f32 v70, s[0:1], v51, v51, 1.0
	v_rcp_f32_e32 v72, v70
	v_div_scale_f32 v71, vcc, 1.0, v51, 1.0
	v_lshlrev_b32_e32 v66, 16, v60
	v_fma_f32 v73, -v70, v72, 1.0
	v_fmac_f32_e32 v72, v73, v72
	v_mul_f32_e32 v73, v71, v72
	v_fma_f32 v74, -v70, v73, v71
	v_fmac_f32_e32 v73, v74, v72
	v_fma_f32 v70, -v70, v73, v71
	v_div_fmas_f32 v70, v70, v72, v73
	v_div_fixup_f32 v70, v70, v51, 1.0
	v_and_b32_e32 v67, 0xffff0000, v60
	v_lshlrev_b32_e32 v60, 16, v61
	v_and_b32_e32 v61, 0xffff0000, v61
	v_pk_mul_f32 v[52:53], v[70:71], v[52:53] op_sel_hi:[0,1]
	v_pk_mul_f32 v[54:55], v[70:71], v[54:55] op_sel_hi:[0,1]
	v_pk_mul_f32 v[62:63], v[70:71], v[62:63] op_sel_hi:[0,1]
	v_pk_mul_f32 v[56:57], v[70:71], v[56:57] op_sel_hi:[0,1]
	v_pk_mul_f32 v[64:65], v[70:71], v[64:65] op_sel_hi:[0,1]
	v_pk_mul_f32 v[72:73], v[70:71], v[58:59] op_sel_hi:[0,1]
	v_pk_mul_f32 v[74:75], v[70:71], v[66:67] op_sel_hi:[0,1]
	v_pk_mul_f32 v[66:67], v[70:71], v[60:61] op_sel_hi:[0,1]
	v_pk_mul_f32 v[54:55], v[2:3], v[54:55]
	v_pk_mul_f32 v[52:53], v[0:1], v[52:53]
	v_pk_mul_f32 v[58:59], v[6:7], v[56:57]
	v_pk_mul_f32 v[56:57], v[4:5], v[62:63]
	v_pk_mul_f32 v[62:63], v[10:11], v[72:73]
	v_pk_mul_f32 v[60:61], v[8:9], v[64:65]
	v_pk_mul_f32 v[66:67], v[14:15], v[66:67]
	v_pk_mul_f32 v[64:65], v[12:13], v[74:75]
	global_store_dwordx4 v[68:69], v[52:55], off
	global_store_dwordx4 v[68:69], v[56:59], off offset:1024
	global_store_dwordx4 v[68:69], v[60:63], off offset:2048
	global_store_dwordx4 v[68:69], v[64:67], off offset:3072
	s_cmp_lg_u32 s16, 0
	s_cbranch_scc0 .Lfn_topA
